# plus: grid barrier non-leaders poll the top-level generation word directly (one relay hop less)
# baseline (speedup 1.0000x reference)
.LBB0_56:
	s_or_b64 exec, exec, s[10:11]
	v_cvt_f32_u32_e32 v4, v2
	s_waitcnt vmcnt(0)
	v_readfirstlane_b32 s3, v3
	v_sub_u32_e32 v3, 0, v2
	v_rcp_iflag_f32_e32 v4, v4
	v_add_u32_e32 v5, s3, v1
	v_mul_f32_e32 v4, 0x4f7ffffe, v4
	v_cvt_u32_f32_e32 v4, v4
	v_mul_lo_u32 v1, v3, v4
	v_mul_hi_u32 v1, v4, v1
	v_add_u32_e32 v1, v4, v1
	v_mul_hi_u32 v1, v5, v1
	v_mul_lo_u32 v3, v1, v2
	v_sub_u32_e32 v3, v5, v3
	v_add_u32_e32 v4, 1, v1
	v_cmp_ge_u32_e32 vcc, v3, v2
	s_nop 1
	v_cndmask_b32_e32 v1, v1, v4, vcc
	v_sub_u32_e32 v4, v3, v2
	v_cndmask_b32_e32 v3, v3, v4, vcc
	v_add_u32_e32 v4, 1, v1
	v_cmp_ge_u32_e32 vcc, v3, v2
	v_add_u32_e32 v3, 1, v5
	s_nop 0
	v_cndmask_b32_e32 v1, v1, v4, vcc
	v_mul_lo_u32 v4, v2, v1
	v_add_u32_e32 v2, v4, v2
	v_cmp_ne_u32_e32 vcc, v3, v2
	s_and_saveexec_b64 s[8:9], vcc
	s_xor_b64 s[8:9], exec, s[8:9]
	s_cbranch_execz .LBB0_70
	s_waitcnt lgkmcnt(0)
	s_add_u32 s18, s0, 0x7500
	s_addc_u32 s19, s1, 0
	v_mov_b32_e32 v0, 0
	global_load_dword v0, v0, s[18:19] sc1
	s_waitcnt vmcnt(0)
	v_cmp_gt_u32_e32 vcc, 1, v0
	s_and_saveexec_b64 s[10:11], vcc
	s_cbranch_execz .LBB0_69
	s_add_u32 s16, s0, 0x4200
	s_addc_u32 s17, s1, 0
	s_mov_b32 s3, 1
	s_mov_b64 s[20:21], 0
	v_mov_b32_e32 v0, 0
	s_branch .LBB0_60

.LBB0_64:
	global_load_dword v2, v0, s[18:19] sc1
	s_add_i32 s3, s3, 1
	s_mov_b64 s[38:39], -1
	s_waitcnt vmcnt(0)
	v_cmp_le_u32_e32 vcc, 1, v2
	s_orn2_b64 s[36:37], vcc, exec
	s_branch .LBB0_59

.LBB0_376:
	s_or_b64 exec, exec, s[10:11]
	v_cvt_f32_u32_e32 v4, v2
	s_waitcnt vmcnt(0)
	v_readfirstlane_b32 s8, v3
	v_sub_u32_e32 v3, 0, v2
	v_rcp_iflag_f32_e32 v4, v4
	v_add_u32_e32 v5, s8, v1
	v_mul_f32_e32 v4, 0x4f7ffffe, v4
	v_cvt_u32_f32_e32 v4, v4
	v_mul_lo_u32 v1, v3, v4
	v_mul_hi_u32 v1, v4, v1
	v_add_u32_e32 v1, v4, v1
	v_mul_hi_u32 v1, v5, v1
	v_mul_lo_u32 v3, v1, v2
	v_sub_u32_e32 v3, v5, v3
	v_add_u32_e32 v4, 1, v1
	v_cmp_ge_u32_e32 vcc, v3, v2
	s_nop 1
	v_cndmask_b32_e32 v1, v1, v4, vcc
	v_sub_u32_e32 v4, v3, v2
	v_cndmask_b32_e32 v3, v3, v4, vcc
	v_add_u32_e32 v4, 1, v1
	v_cmp_ge_u32_e32 vcc, v3, v2
	v_add_u32_e32 v3, 1, v5
	s_nop 0
	v_cndmask_b32_e32 v1, v1, v4, vcc
	v_mul_lo_u32 v4, v2, v1
	v_add_u32_e32 v2, v4, v2
	v_cmp_ne_u32_e32 vcc, v3, v2
	s_and_saveexec_b64 s[8:9], vcc
	s_xor_b64 s[8:9], exec, s[8:9]
	s_cbranch_execz .LBB0_390
	s_waitcnt lgkmcnt(0)
	s_add_u32 s18, s0, 0x7500
	s_addc_u32 s19, s1, 0
	v_mov_b32_e32 v0, 0
	global_load_dword v0, v0, s[18:19] sc1
	s_waitcnt vmcnt(0)
	v_cmp_gt_u32_e32 vcc, 2, v0
	s_and_saveexec_b64 s[10:11], vcc
	s_cbranch_execz .LBB0_389
	s_add_u32 s16, s0, 0x4200
	s_addc_u32 s17, s1, 0
	s_mov_b32 s13, 1
	s_mov_b64 s[20:21], 0
	v_mov_b32_e32 v0, 0
	s_branch .LBB0_380

.LBB0_384:
	global_load_dword v2, v0, s[18:19] sc1
	s_add_i32 s13, s13, 1
	s_mov_b64 s[42:43], -1
	s_waitcnt vmcnt(0)
	v_cmp_le_u32_e32 vcc, 2, v2
	s_orn2_b64 s[40:41], vcc, exec
	s_branch .LBB0_379

.LBB0_613:
	s_or_b64 exec, exec, s[12:13]
	v_cvt_f32_u32_e32 v4, v2
	s_waitcnt vmcnt(0)
	v_readfirstlane_b32 s10, v3
	v_sub_u32_e32 v3, 0, v2
	v_rcp_iflag_f32_e32 v4, v4
	v_add_u32_e32 v5, s10, v1
	v_mul_f32_e32 v4, 0x4f7ffffe, v4
	v_cvt_u32_f32_e32 v4, v4
	v_mul_lo_u32 v1, v3, v4
	v_mul_hi_u32 v1, v4, v1
	v_add_u32_e32 v1, v4, v1
	v_mul_hi_u32 v1, v5, v1
	v_mul_lo_u32 v3, v1, v2
	v_sub_u32_e32 v3, v5, v3
	v_add_u32_e32 v4, 1, v1
	v_cmp_ge_u32_e32 vcc, v3, v2
	s_nop 1
	v_cndmask_b32_e32 v1, v1, v4, vcc
	v_sub_u32_e32 v4, v3, v2
	v_cndmask_b32_e32 v3, v3, v4, vcc
	v_add_u32_e32 v4, 1, v1
	v_cmp_ge_u32_e32 vcc, v3, v2
	v_add_u32_e32 v3, 1, v5
	s_nop 0
	v_cndmask_b32_e32 v1, v1, v4, vcc
	v_mul_lo_u32 v4, v2, v1
	v_add_u32_e32 v2, v4, v2
	v_cmp_ne_u32_e32 vcc, v3, v2
	s_and_saveexec_b64 s[10:11], vcc
	s_xor_b64 s[10:11], exec, s[10:11]
	s_cbranch_execz .LBB0_627
	s_waitcnt lgkmcnt(0)
	s_add_u32 s18, s0, 0x7500
	s_addc_u32 s19, s1, 0
	v_mov_b32_e32 v0, 0
	global_load_dword v0, v0, s[18:19] sc1
	s_waitcnt vmcnt(0)
	v_cmp_gt_u32_e32 vcc, 3, v0
	s_and_saveexec_b64 s[12:13], vcc
	s_cbranch_execz .LBB0_626
	s_add_u32 s16, s0, 0x4200
	s_addc_u32 s17, s1, 0
	s_mov_b32 s14, 1
	s_mov_b64 s[20:21], 0
	v_mov_b32_e32 v0, 0
	s_branch .LBB0_617

.LBB0_621:
	global_load_dword v2, v0, s[18:19] sc1
	s_add_i32 s14, s14, 1
	s_mov_b64 s[42:43], -1
	s_waitcnt vmcnt(0)
	v_cmp_le_u32_e32 vcc, 3, v2
	s_orn2_b64 s[40:41], vcc, exec
	s_branch .LBB0_616

.LBB0_794:
	s_or_b64 exec, exec, s[16:17]
	v_cvt_f32_u32_e32 v4, v2
	s_waitcnt vmcnt(0)
	v_readfirstlane_b32 s12, v3
	v_sub_u32_e32 v3, 0, v2
	v_rcp_iflag_f32_e32 v4, v4
	v_add_u32_e32 v5, s12, v1
	v_mul_f32_e32 v4, 0x4f7ffffe, v4
	v_cvt_u32_f32_e32 v4, v4
	v_mul_lo_u32 v1, v3, v4
	v_mul_hi_u32 v1, v4, v1
	v_add_u32_e32 v1, v4, v1
	v_mul_hi_u32 v1, v5, v1
	v_mul_lo_u32 v3, v1, v2
	v_sub_u32_e32 v3, v5, v3
	v_add_u32_e32 v4, 1, v1
	v_cmp_ge_u32_e32 vcc, v3, v2
	s_nop 1
	v_cndmask_b32_e32 v1, v1, v4, vcc
	v_sub_u32_e32 v4, v3, v2
	v_cndmask_b32_e32 v3, v3, v4, vcc
	v_add_u32_e32 v4, 1, v1
	v_cmp_ge_u32_e32 vcc, v3, v2
	v_add_u32_e32 v3, 1, v5
	s_nop 0
	v_cndmask_b32_e32 v1, v1, v4, vcc
	v_mul_lo_u32 v4, v2, v1
	v_add_u32_e32 v2, v4, v2
	v_cmp_ne_u32_e32 vcc, v3, v2
	s_and_saveexec_b64 s[12:13], vcc
	s_xor_b64 s[12:13], exec, s[12:13]
	s_cbranch_execz .LBB0_808
	s_waitcnt lgkmcnt(0)
	s_add_u32 s18, s0, 0x7500
	s_addc_u32 s19, s1, 0
	v_mov_b32_e32 v0, 0
	global_load_dword v0, v0, s[18:19] sc1
	s_waitcnt vmcnt(0)
	v_cmp_gt_u32_e32 vcc, 4, v0
	s_and_saveexec_b64 s[16:17], vcc
	s_cbranch_execz .LBB0_807
	s_mov_b32 s14, 1
	s_mov_b64 s[22:23], 0
	v_mov_b32_e32 v0, 0
	s_branch .LBB0_798

.LBB0_802:
	global_load_dword v2, v0, s[18:19] sc1
	s_add_i32 s14, s14, 1
	s_mov_b64 s[46:47], -1
	s_waitcnt vmcnt(0)
	v_cmp_le_u32_e32 vcc, 4, v2
	s_orn2_b64 s[44:45], vcc, exec
	s_branch .LBB0_797

.LBB0_902:
	s_or_b64 exec, exec, s[16:17]
	v_cvt_f32_u32_e32 v4, v2
	s_waitcnt vmcnt(0)
	v_readfirstlane_b32 s12, v3
	v_sub_u32_e32 v3, 0, v2
	v_rcp_iflag_f32_e32 v4, v4
	v_add_u32_e32 v5, s12, v1
	v_mul_f32_e32 v4, 0x4f7ffffe, v4
	v_cvt_u32_f32_e32 v4, v4
	v_mul_lo_u32 v1, v3, v4
	v_mul_hi_u32 v1, v4, v1
	v_add_u32_e32 v1, v4, v1
	v_mul_hi_u32 v1, v5, v1
	v_mul_lo_u32 v3, v1, v2
	v_sub_u32_e32 v3, v5, v3
	v_add_u32_e32 v4, 1, v1
	v_cmp_ge_u32_e32 vcc, v3, v2
	s_nop 1
	v_cndmask_b32_e32 v1, v1, v4, vcc
	v_sub_u32_e32 v4, v3, v2
	v_cndmask_b32_e32 v3, v3, v4, vcc
	v_add_u32_e32 v4, 1, v1
	v_cmp_ge_u32_e32 vcc, v3, v2
	v_add_u32_e32 v3, 1, v5
	s_nop 0
	v_cndmask_b32_e32 v1, v1, v4, vcc
	v_mul_lo_u32 v4, v2, v1
	v_add_u32_e32 v2, v4, v2
	v_cmp_ne_u32_e32 vcc, v3, v2
	s_and_saveexec_b64 s[12:13], vcc
	s_xor_b64 s[12:13], exec, s[12:13]
	s_cbranch_execz .LBB0_916
	s_waitcnt lgkmcnt(0)
	s_add_u32 s18, s0, 0x7500
	s_addc_u32 s19, s1, 0
	v_mov_b32_e32 v0, 0
	global_load_dword v0, v0, s[18:19] sc1
	s_waitcnt vmcnt(0)
	v_cmp_gt_u32_e32 vcc, 5, v0
	s_and_saveexec_b64 s[16:17], vcc
	s_cbranch_execz .LBB0_915
	s_mov_b32 s14, 1
	s_mov_b64 s[22:23], 0
	v_mov_b32_e32 v0, 0
	s_branch .LBB0_906

.LBB0_910:
	global_load_dword v2, v0, s[18:19] sc1
	s_add_i32 s14, s14, 1
	s_mov_b64 s[42:43], -1
	s_waitcnt vmcnt(0)
	v_cmp_le_u32_e32 vcc, 5, v2
	s_orn2_b64 s[40:41], vcc, exec
	s_branch .LBB0_905

.LBB0_1024:
	s_or_b64 exec, exec, s[12:13]
	v_cvt_f32_u32_e32 v4, v2
	s_waitcnt vmcnt(0)
	v_readfirstlane_b32 s10, v3
	v_sub_u32_e32 v3, 0, v2
	v_rcp_iflag_f32_e32 v4, v4
	v_add_u32_e32 v5, s10, v1
	v_mul_f32_e32 v4, 0x4f7ffffe, v4
	v_cvt_u32_f32_e32 v4, v4
	v_mul_lo_u32 v1, v3, v4
	v_mul_hi_u32 v1, v4, v1
	v_add_u32_e32 v1, v4, v1
	v_mul_hi_u32 v1, v5, v1
	v_mul_lo_u32 v3, v1, v2
	v_sub_u32_e32 v3, v5, v3
	v_add_u32_e32 v4, 1, v1
	v_cmp_ge_u32_e32 vcc, v3, v2
	s_nop 1
	v_cndmask_b32_e32 v1, v1, v4, vcc
	v_sub_u32_e32 v4, v3, v2
	v_cndmask_b32_e32 v3, v3, v4, vcc
	v_add_u32_e32 v4, 1, v1
	v_cmp_ge_u32_e32 vcc, v3, v2
	v_add_u32_e32 v3, 1, v5
	s_nop 0
	v_cndmask_b32_e32 v1, v1, v4, vcc
	v_mul_lo_u32 v4, v2, v1
	v_add_u32_e32 v2, v4, v2
	v_cmp_ne_u32_e32 vcc, v3, v2
	s_and_saveexec_b64 s[10:11], vcc
	s_xor_b64 s[10:11], exec, s[10:11]
	s_cbranch_execz .LBB0_1038
	s_waitcnt lgkmcnt(0)
	s_add_u32 s16, s0, 0x7500
	s_addc_u32 s17, s1, 0
	v_mov_b32_e32 v0, 0
	global_load_dword v0, v0, s[16:17] sc1
	s_waitcnt vmcnt(0)
	v_cmp_gt_u32_e32 vcc, 6, v0
	s_and_saveexec_b64 s[12:13], vcc
	s_cbranch_execz .LBB0_1037
	s_mov_b32 s14, 1
	s_mov_b64 s[18:19], 0
	v_mov_b32_e32 v0, 0
	s_branch .LBB0_1028

.LBB0_1032:
	global_load_dword v2, v0, s[16:17] sc1
	s_add_i32 s14, s14, 1
	s_mov_b64 s[28:29], -1
	s_waitcnt vmcnt(0)
	v_cmp_le_u32_e32 vcc, 6, v2
	s_orn2_b64 s[26:27], vcc, exec
	s_branch .LBB0_1027
